# G2 row-scale table build: partial-sum loads of the workgroup's units 1-3 issued together with unit 0's, counted vmcnt waits instead of one load round trip per unit
# baseline (speedup 1.0000x reference)
.LBB0_600:
	s_cmp_gt_i32 s88, 3
	s_cselect_b64 s[2:3], -1, 0
	s_xor_b64 s[0:1], s[0:1], -1
	s_or_b64 s[0:1], s[2:3], s[0:1]
	s_and_b64 vcc, exec, s[0:1]
	s_cbranch_vccnz .LBB0_962
	v_readlane_b32 s0, v249, 0
	s_ashr_i32 s24, s96, 31
	s_ashr_i32 s25, s0, 31
	s_cmpk_lt_i32 s0, 0x408
	v_lshlrev_b32_e32 v1, 2, v188
	s_cselect_b64 s[6:7], -1, 0
	s_cmpk_gt_i32 s0, 0x407
	v_lshlrev_b32_e32 v156, 3, v188
	s_cbranch_scc1 .LBB0_619
	s_add_u32 s8, s30, 0x2ac00000
	s_movk_i32 s0, 0xff
	s_movk_i32 s2, 0x100
	s_addc_u32 s9, s31, 0
	v_cmp_lt_u32_e64 s[0:1], s0, v188
	v_cmp_gt_u32_e64 s[2:3], s2, v188
	s_and_saveexec_b64 s[10:11], s[2:3]
	s_cbranch_execz .LBB0_604
	s_lshr_b32 s4, s25, 29
	v_readlane_b32 s12, v249, 0
	s_add_i32 s4, s12, s4
	s_and_b32 s5, s4, -8
	s_sub_i32 s5, s12, s5
	s_cmp_lt_i32 s5, 0
	s_movk_i32 s12, 0x82
	s_movk_i32 s12, 0x80
	s_mul_i32 s5, s5, s12
	s_ashr_i32 s4, s4, 3
	s_add_i32 s4, s5, s4
	s_ashr_i32 s5, s4, 31
	s_lshr_b32 s5, s5, 27
	s_add_i32 s5, s4, s5
	s_ashr_i32 s12, s5, 5
	s_lshl_b32 s12, s12, 3
	s_andn2_b32 s5, s5, 31
	s_sub_i32 s13, s4, s5
	s_sub_i32 s4, 0x102, s12
	s_min_u32 s14, s4, 8
	v_cvt_f32_ubyte0_e32 v2, s14
	v_cvt_f32_i32_e32 v0, s13
	v_rcp_iflag_f32_e32 v3, v2
	s_ashr_i32 s4, s13, 30
	s_or_b32 s15, s4, 1
	v_mul_f32_e32 v3, v0, v3
	v_trunc_f32_e32 v3, v3
	v_fma_f32 v0, -v3, v2, v0
	v_cvt_i32_f32_e32 v3, v3
	v_cmp_ge_f32_e64 s[4:5], |v0|, v2
	s_and_b64 s[4:5], s[4:5], exec
	s_cselect_b32 s4, s15, 0
	v_readfirstlane_b32 s5, v3
	s_add_i32 s4, s5, s4
	s_mul_i32 s4, s4, s14
	s_sub_i32 s4, s13, s4
	s_sext_i32_i8 s4, s4
	s_add_i32 s12, s12, s4
	v_lshl_or_b32 v2, s12, 10, v1
	v_ashrrev_i32_e32 v3, 31, v2
	s_waitcnt lgkmcnt(0)
	v_lshl_add_u64 v[18:19], v[2:3], 4, s[8:9]
	global_load_dwordx4 v[2:5], v[18:19], off
	global_load_dwordx4 v[6:9], v[18:19], off offset:16
	global_load_dwordx4 v[10:13], v[18:19], off offset:32
	global_load_dwordx4 v[14:17], v[18:19], off offset:48
	s_mov_b64 s[32:33], 0x20000
	s_mov_b64 s[34:35], 0x40000
	s_mov_b64 s[36:37], 0x60000
	v_lshl_add_u64 v[68:69], v[18:19], 0, s[32:33]
	global_load_dwordx4 v[20:23], v[68:69], off
	global_load_dwordx4 v[24:27], v[68:69], off offset:16
	global_load_dwordx4 v[28:31], v[68:69], off offset:32
	global_load_dwordx4 v[32:35], v[68:69], off offset:48
	v_lshl_add_u64 v[68:69], v[18:19], 0, s[34:35]
	global_load_dwordx4 v[36:39], v[68:69], off
	global_load_dwordx4 v[40:43], v[68:69], off offset:16
	global_load_dwordx4 v[44:47], v[68:69], off offset:32
	global_load_dwordx4 v[48:51], v[68:69], off offset:48
	v_lshl_add_u64 v[68:69], v[18:19], 0, s[36:37]
	global_load_dwordx4 v[52:55], v[68:69], off
	global_load_dwordx4 v[56:59], v[68:69], off offset:16
	global_load_dwordx4 v[60:63], v[68:69], off offset:32
	global_load_dwordx4 v[64:67], v[68:69], off offset:48
	v_mov_b32_e32 v0, 0x358637bd
	s_waitcnt vmcnt(12)
	v_add_f32_e32 v2, v2, v3
	v_add_f32_e32 v3, v4, v5
	v_add_f32_e32 v4, v6, v7
	v_add_f32_e32 v5, v8, v9
	v_add_f32_e32 v6, v10, v11
	v_add_f32_e32 v7, v12, v13
	v_add_f32_e32 v8, v14, v15
	v_add_f32_e32 v9, v16, v17
	v_add_f32_e32 v2, v2, v3
	v_add_f32_e32 v3, v4, v5
	v_add_f32_e32 v4, v6, v7
	v_add_f32_e32 v5, v8, v9
	v_add_f32_e32 v2, v2, v3
	v_add_f32_e32 v3, v4, v5
	v_fmamk_f32 v2, v2, 0x3b000000, v0
	v_fmac_f32_e32 v0, 0x3b000000, v3
	v_div_scale_f32 v3, s[4:5], v2, v2, v0
	v_rcp_f32_e32 v4, v3
	v_div_scale_f32 v5, vcc, v0, v2, v0
	s_mov_b32 s4, 0xf800000
	v_fma_f32 v6, -v3, v4, 1.0
	v_fmac_f32_e32 v4, v6, v4
	v_mul_f32_e32 v6, v5, v4
	v_fma_f32 v7, -v3, v6, v5
	v_fmac_f32_e32 v6, v7, v4
	v_fma_f32 v3, -v3, v6, v5
	v_div_fmas_f32 v3, v3, v4, v6
	v_div_fixup_f32 v2, v3, v2, v0
	v_mul_f32_e32 v3, 0x4f800000, v2
	v_cmp_gt_f32_e32 vcc, s4, v2
	v_mov_b32_e32 v5, 0x260
	v_add_u32_e32 v6, 0, v156
	v_cndmask_b32_e32 v2, v2, v3, vcc
	v_sqrt_f32_e32 v4, v2
	v_rsq_f32_e32 v3, v0
	v_add_u32_e32 v0, -1, v4
	v_add_u32_e32 v7, 1, v4
	v_fma_f32 v8, -v0, v4, v2
	v_fma_f32 v9, -v7, v4, v2
	v_cmp_ge_f32_e64 s[4:5], 0, v8
	s_nop 1
	v_cndmask_b32_e64 v0, v4, v0, s[4:5]
	v_cmp_lt_f32_e64 s[4:5], 0, v9
	s_nop 1
	v_cndmask_b32_e64 v0, v0, v7, s[4:5]
	v_mul_f32_e32 v4, 0x37800000, v0
	v_cndmask_b32_e32 v0, v0, v4, vcc
	v_cmp_class_f32_e32 vcc, v2, v5
	s_nop 1
	v_cndmask_b32_e32 v2, v0, v2, vcc
	v_add_u32_e32 v0, 0x20000, v6
	ds_write_b64 v0, v[2:3]
.LBB0_604:
	s_or_b64 exec, exec, s[10:11]
	v_readlane_b32 s4, v249, 0
	s_add_u32 s10, s96, s4
	s_addc_u32 s11, s24, s25
	v_mov_b64_e32 v[2:3], 0x407
	v_cmp_gt_i64_e32 vcc, s[10:11], v[2:3]
	s_cbranch_vccnz .LBB0_619
	s_and_saveexec_b64 s[12:13], s[2:3]
	s_cbranch_execz .LBB0_607
	s_ashr_i32 s4, s10, 31
	s_lshr_b32 s4, s4, 29
	s_add_i32 s4, s10, s4
	s_ashr_i32 s5, s4, 3
	s_and_b32 s4, s4, -8
	s_sub_i32 s4, s10, s4
	s_cmp_lt_i32 s4, 0
	s_movk_i32 s14, 0x82
	s_movk_i32 s14, 0x80
	s_mul_i32 s4, s4, s14
	s_add_i32 s4, s4, s5
	s_ashr_i32 s5, s4, 31
	s_lshr_b32 s5, s5, 27
	s_add_i32 s5, s4, s5
	s_ashr_i32 s14, s5, 5
	s_lshl_b32 s14, s14, 3
	s_sub_i32 s15, 0x102, s14
	s_min_i32 s15, s15, 8
	s_abs_i32 s15, s15
	v_cvt_f32_u32_e32 v0, s15
	s_sub_i32 s16, 0, s15
	s_andn2_b32 s5, s5, 31
	s_sub_i32 s4, s4, s5
	v_rcp_iflag_f32_e32 v0, v0
	s_ashr_i32 s5, s4, 31
	s_abs_i32 s4, s4
	v_mul_f32_e32 v0, 0x4f7ffffe, v0
	v_cvt_u32_f32_e32 v0, v0
	s_nop 0
	v_readfirstlane_b32 s17, v0
	s_mul_i32 s16, s16, s17
	s_mul_hi_u32 s16, s17, s16
	s_add_i32 s17, s17, s16
	s_mul_hi_u32 s16, s4, s17
	s_mul_i32 s16, s16, s15
	s_sub_i32 s4, s4, s16
	s_sub_i32 s16, s4, s15
	s_cmp_ge_u32 s4, s15
	s_cselect_b32 s4, s16, s4
	s_sub_i32 s16, s4, s15
	s_cmp_ge_u32 s4, s15
	s_cselect_b32 s4, s16, s4
	s_xor_b32 s4, s4, s5
	s_sub_i32 s4, s4, s5
	s_add_i32 s14, s14, s4
	v_lshl_or_b32 v2, s14, 10, v1
	v_ashrrev_i32_e32 v3, 31, v2
	v_lshl_add_u64 v[14:15], v[2:3], 4, s[8:9]
	s_nop 0
	s_nop 0
	s_nop 0
	s_nop 0
	s_nop 0
	v_mov_b32_e32 v0, 0x358637bd
	s_add_i32 s14, 0, 0x20000
	s_waitcnt vmcnt(8)
	v_add_f32_e32 v2, v20, v21
	v_add_f32_e32 v3, v22, v23
	v_add_f32_e32 v4, v24, v25
	v_add_f32_e32 v5, v26, v27
	v_add_f32_e32 v6, v28, v29
	v_add_f32_e32 v7, v30, v31
	v_add_f32_e32 v8, v32, v33
	v_add_f32_e32 v9, v34, v35
	v_add_f32_e32 v2, v2, v3
	v_add_f32_e32 v3, v4, v5
	v_add_f32_e32 v4, v6, v7
	v_add_f32_e32 v5, v8, v9
	v_add_f32_e32 v2, v2, v3
	v_add_f32_e32 v3, v4, v5
	v_fmamk_f32 v2, v2, 0x3b000000, v0
	v_fmac_f32_e32 v0, 0x3b000000, v3
	v_div_scale_f32 v3, s[4:5], v2, v2, v0
	v_rcp_f32_e32 v4, v3
	v_div_scale_f32 v5, vcc, v0, v2, v0
	s_mov_b32 s4, 0xf800000
	v_fma_f32 v6, -v3, v4, 1.0
	v_fmac_f32_e32 v4, v6, v4
	v_mul_f32_e32 v6, v5, v4
	v_fma_f32 v7, -v3, v6, v5
	v_fmac_f32_e32 v6, v7, v4
	v_fma_f32 v3, -v3, v6, v5
	v_div_fmas_f32 v3, v3, v4, v6
	v_div_fixup_f32 v2, v3, v2, v0
	v_mul_f32_e32 v3, 0x4f800000, v2
	v_cmp_gt_f32_e32 vcc, s4, v2
	v_mov_b32_e32 v5, 0x260
	s_nop 0
	v_cndmask_b32_e32 v2, v2, v3, vcc
	v_sqrt_f32_e32 v4, v2
	v_rsq_f32_e32 v3, v0
	v_add_u32_e32 v0, -1, v4
	v_add_u32_e32 v6, 1, v4
	v_fma_f32 v7, -v0, v4, v2
	v_fma_f32 v8, -v6, v4, v2
	v_cmp_ge_f32_e64 s[4:5], 0, v7
	s_nop 1
	v_cndmask_b32_e64 v0, v4, v0, s[4:5]
	v_cmp_lt_f32_e64 s[4:5], 0, v8
	s_nop 1
	v_cndmask_b32_e64 v0, v0, v6, s[4:5]
	v_mul_f32_e32 v4, 0x37800000, v0
	v_cndmask_b32_e32 v0, v0, v4, vcc
	v_cmp_class_f32_e32 vcc, v2, v5
	s_nop 1
	v_cndmask_b32_e32 v2, v0, v2, vcc
	v_add_u32_e32 v0, s14, v156
	ds_write_b64 v0, v[2:3] offset:2048
.LBB0_607:
	s_or_b64 exec, exec, s[12:13]
	s_add_u32 s10, s10, s96
	s_addc_u32 s11, s11, s24
	v_mov_b64_e32 v[2:3], 0x407
	v_cmp_gt_i64_e32 vcc, s[10:11], v[2:3]
	s_cbranch_vccnz .LBB0_619
	s_and_saveexec_b64 s[12:13], s[2:3]
	s_cbranch_execz .LBB0_610
	s_ashr_i32 s4, s10, 31
	s_lshr_b32 s4, s4, 29
	s_add_i32 s4, s10, s4
	s_ashr_i32 s5, s4, 3
	s_and_b32 s4, s4, -8
	s_sub_i32 s4, s10, s4
	s_cmp_lt_i32 s4, 0
	s_movk_i32 s14, 0x82
	s_movk_i32 s14, 0x80
	s_mul_i32 s4, s4, s14
	s_add_i32 s4, s4, s5
	s_ashr_i32 s5, s4, 31
	s_lshr_b32 s5, s5, 27
	s_add_i32 s5, s4, s5
	s_ashr_i32 s14, s5, 5
	s_lshl_b32 s14, s14, 3
	s_sub_i32 s15, 0x102, s14
	s_min_i32 s15, s15, 8
	s_abs_i32 s15, s15
	v_cvt_f32_u32_e32 v0, s15
	s_sub_i32 s16, 0, s15
	s_andn2_b32 s5, s5, 31
	s_sub_i32 s4, s4, s5
	v_rcp_iflag_f32_e32 v0, v0
	s_ashr_i32 s5, s4, 31
	s_abs_i32 s4, s4
	v_mul_f32_e32 v0, 0x4f7ffffe, v0
	v_cvt_u32_f32_e32 v0, v0
	s_nop 0
	v_readfirstlane_b32 s17, v0
	s_mul_i32 s16, s16, s17
	s_mul_hi_u32 s16, s17, s16
	s_add_i32 s17, s17, s16
	s_mul_hi_u32 s16, s4, s17
	s_mul_i32 s16, s16, s15
	s_sub_i32 s4, s4, s16
	s_sub_i32 s16, s4, s15
	s_cmp_ge_u32 s4, s15
	s_cselect_b32 s4, s16, s4
	s_sub_i32 s16, s4, s15
	s_cmp_ge_u32 s4, s15
	s_cselect_b32 s4, s16, s4
	s_xor_b32 s4, s4, s5
	s_sub_i32 s4, s4, s5
	s_add_i32 s14, s14, s4
	v_lshl_or_b32 v2, s14, 10, v1
	v_ashrrev_i32_e32 v3, 31, v2
	v_lshl_add_u64 v[14:15], v[2:3], 4, s[8:9]
	s_nop 0
	s_nop 0
	s_nop 0
	s_nop 0
	s_nop 0
	v_mov_b32_e32 v0, 0x358637bd
	s_add_i32 s14, 0, 0x20000
	s_waitcnt vmcnt(4)
	v_add_f32_e32 v2, v36, v37
	v_add_f32_e32 v3, v38, v39
	v_add_f32_e32 v4, v40, v41
	v_add_f32_e32 v5, v42, v43
	v_add_f32_e32 v6, v44, v45
	v_add_f32_e32 v7, v46, v47
	v_add_f32_e32 v8, v48, v49
	v_add_f32_e32 v9, v50, v51
	v_add_f32_e32 v2, v2, v3
	v_add_f32_e32 v3, v4, v5
	v_add_f32_e32 v4, v6, v7
	v_add_f32_e32 v5, v8, v9
	v_add_f32_e32 v2, v2, v3
	v_add_f32_e32 v3, v4, v5
	v_fmamk_f32 v2, v2, 0x3b000000, v0
	v_fmac_f32_e32 v0, 0x3b000000, v3
	v_div_scale_f32 v3, s[4:5], v2, v2, v0
	v_rcp_f32_e32 v4, v3
	v_div_scale_f32 v5, vcc, v0, v2, v0
	s_mov_b32 s4, 0xf800000
	v_fma_f32 v6, -v3, v4, 1.0
	v_fmac_f32_e32 v4, v6, v4
	v_mul_f32_e32 v6, v5, v4
	v_fma_f32 v7, -v3, v6, v5
	v_fmac_f32_e32 v6, v7, v4
	v_fma_f32 v3, -v3, v6, v5
	v_div_fmas_f32 v3, v3, v4, v6
	v_div_fixup_f32 v2, v3, v2, v0
	v_mul_f32_e32 v3, 0x4f800000, v2
	v_cmp_gt_f32_e32 vcc, s4, v2
	v_mov_b32_e32 v5, 0x260
	s_nop 0
	v_cndmask_b32_e32 v2, v2, v3, vcc
	v_sqrt_f32_e32 v4, v2
	v_rsq_f32_e32 v3, v0
	v_add_u32_e32 v0, -1, v4
	v_add_u32_e32 v6, 1, v4
	v_fma_f32 v7, -v0, v4, v2
	v_fma_f32 v8, -v6, v4, v2
	v_cmp_ge_f32_e64 s[4:5], 0, v7
	s_nop 1
	v_cndmask_b32_e64 v0, v4, v0, s[4:5]
	v_cmp_lt_f32_e64 s[4:5], 0, v8
	s_nop 1
	v_cndmask_b32_e64 v0, v0, v6, s[4:5]
	v_mul_f32_e32 v4, 0x37800000, v0
	v_cndmask_b32_e32 v0, v0, v4, vcc
	v_cmp_class_f32_e32 vcc, v2, v5
	s_nop 1
	v_cndmask_b32_e32 v2, v0, v2, vcc
	v_add_u32_e32 v0, s14, v156
	ds_write_b64 v0, v[2:3] offset:4096
.LBB0_610:
	s_or_b64 exec, exec, s[12:13]
	s_add_u32 s10, s10, s96
	s_addc_u32 s11, s11, s24
	v_mov_b64_e32 v[2:3], 0x407
	v_cmp_gt_i64_e32 vcc, s[10:11], v[2:3]
	s_cbranch_vccnz .LBB0_619
	s_and_saveexec_b64 s[12:13], s[2:3]
	s_cbranch_execz .LBB0_613
	s_ashr_i32 s4, s10, 31
	s_lshr_b32 s4, s4, 29
	s_add_i32 s4, s10, s4
	s_ashr_i32 s5, s4, 3
	s_and_b32 s4, s4, -8
	s_sub_i32 s4, s10, s4
	s_cmp_lt_i32 s4, 0
	s_movk_i32 s14, 0x82
	s_movk_i32 s14, 0x80
	s_mul_i32 s4, s4, s14
	s_add_i32 s4, s4, s5
	s_ashr_i32 s5, s4, 31
	s_lshr_b32 s5, s5, 27
	s_add_i32 s5, s4, s5
	s_ashr_i32 s14, s5, 5
	s_lshl_b32 s14, s14, 3
	s_sub_i32 s15, 0x102, s14
	s_min_i32 s15, s15, 8
	s_abs_i32 s15, s15
	v_cvt_f32_u32_e32 v0, s15
	s_sub_i32 s16, 0, s15
	s_andn2_b32 s5, s5, 31
	s_sub_i32 s4, s4, s5
	v_rcp_iflag_f32_e32 v0, v0
	s_ashr_i32 s5, s4, 31
	s_abs_i32 s4, s4
	v_mul_f32_e32 v0, 0x4f7ffffe, v0
	v_cvt_u32_f32_e32 v0, v0
	s_nop 0
	v_readfirstlane_b32 s17, v0
	s_mul_i32 s16, s16, s17
	s_mul_hi_u32 s16, s17, s16
	s_add_i32 s17, s17, s16
	s_mul_hi_u32 s16, s4, s17
	s_mul_i32 s16, s16, s15
	s_sub_i32 s4, s4, s16
	s_sub_i32 s16, s4, s15
	s_cmp_ge_u32 s4, s15
	s_cselect_b32 s4, s16, s4
	s_sub_i32 s16, s4, s15
	s_cmp_ge_u32 s4, s15
	s_cselect_b32 s4, s16, s4
	s_xor_b32 s4, s4, s5
	s_sub_i32 s4, s4, s5
	s_add_i32 s14, s14, s4
	v_lshl_or_b32 v2, s14, 10, v1
	v_ashrrev_i32_e32 v3, 31, v2
	v_lshl_add_u64 v[14:15], v[2:3], 4, s[8:9]
	s_nop 0
	s_nop 0
	s_nop 0
	s_nop 0
	s_nop 0
	v_mov_b32_e32 v0, 0x358637bd
	s_add_i32 s14, 0, 0x20000
	s_waitcnt vmcnt(0)
	v_add_f32_e32 v2, v52, v53
	v_add_f32_e32 v3, v54, v55
	v_add_f32_e32 v4, v56, v57
	v_add_f32_e32 v5, v58, v59
	v_add_f32_e32 v6, v60, v61
	v_add_f32_e32 v7, v62, v63
	v_add_f32_e32 v8, v64, v65
	v_add_f32_e32 v9, v66, v67
	v_add_f32_e32 v2, v2, v3
	v_add_f32_e32 v3, v4, v5
	v_add_f32_e32 v4, v6, v7
	v_add_f32_e32 v5, v8, v9
	v_add_f32_e32 v2, v2, v3
	v_add_f32_e32 v3, v4, v5
	v_fmamk_f32 v2, v2, 0x3b000000, v0
	v_fmac_f32_e32 v0, 0x3b000000, v3
	v_div_scale_f32 v3, s[4:5], v2, v2, v0
	v_rcp_f32_e32 v4, v3
	v_div_scale_f32 v5, vcc, v0, v2, v0
	s_mov_b32 s4, 0xf800000
	v_fma_f32 v6, -v3, v4, 1.0
	v_fmac_f32_e32 v4, v6, v4
	v_mul_f32_e32 v6, v5, v4
	v_fma_f32 v7, -v3, v6, v5
	v_fmac_f32_e32 v6, v7, v4
	v_fma_f32 v3, -v3, v6, v5
	v_div_fmas_f32 v3, v3, v4, v6
	v_div_fixup_f32 v2, v3, v2, v0
	v_mul_f32_e32 v3, 0x4f800000, v2
	v_cmp_gt_f32_e32 vcc, s4, v2
	v_mov_b32_e32 v5, 0x260
	s_nop 0
	v_cndmask_b32_e32 v2, v2, v3, vcc
	v_sqrt_f32_e32 v4, v2
	v_rsq_f32_e32 v3, v0
	v_add_u32_e32 v0, -1, v4
	v_add_u32_e32 v6, 1, v4
	v_fma_f32 v7, -v0, v4, v2
	v_fma_f32 v8, -v6, v4, v2
	v_cmp_ge_f32_e64 s[4:5], 0, v7
	s_nop 1
	v_cndmask_b32_e64 v0, v4, v0, s[4:5]
	v_cmp_lt_f32_e64 s[4:5], 0, v8
	s_nop 1
	v_cndmask_b32_e64 v0, v0, v6, s[4:5]
	v_mul_f32_e32 v4, 0x37800000, v0
	v_cndmask_b32_e32 v0, v0, v4, vcc
	v_cmp_class_f32_e32 vcc, v2, v5
	s_nop 1
	v_cndmask_b32_e32 v2, v0, v2, vcc
	v_add_u32_e32 v0, s14, v156
	ds_write_b64 v0, v[2:3] offset:6144
